# plusU
# speedup vs baseline: 1.0083x; 1.0083x over previous
; #define PG8_STAGE(bufoff, gbase, voff) do { _Pragma("unroll") for (int _i = 0; _i < 2; ++_i) \
;         __builtin_amdgcn_global_load_lds((const unsigned*)((const char*)(gbase) + (voff)[_i]), (PG8_LAS unsigned*)(lds + (bufoff) + ldsw + _i * 8192), 16, 0, 0); } while (0)
; #define PG8_LDA(dst, b, h) do { _Pragma("unroll") for (int m = 0; m < 4; ++m) _Pragma("unroll") for (int k = 0; k < 2; ++k) dst[m][k] = *(const PG8_LAS bf16x8*)(lds + PG8_SA(b, h) + aoff + m * 2048 + k * 1024); } while (0)
; #define PG8_LDB(dst, b, h) do { _Pragma("unroll") for (int n = 0; n < 2; ++n) _Pragma("unroll") for (int k = 0; k < 2; ++k) dst[n][k] = *(const PG8_LAS bf16x8*)(lds + PG8_SB(b, h) + boff + n * 2048 + k * 1024); } while (0)
; #define PG8_MMA(ai, bj, At, Bt) do { __builtin_amdgcn_s_setprio(1); _Pragma("unroll") for (int m = 0; m < 4; ++m) _Pragma("unroll") for (int n = 0; n < 2; ++n) _Pragma("unroll") for (int k = 0; k < 2; ++k) \
;         acc[ai][bj][m][n] = __builtin_amdgcn_mfma_f32_16x16x32_bf16(Bt[n][k], At[m][k], acc[ai][bj][m][n], 0, 0, 0); __builtin_amdgcn_s_setprio(0); } while (0)
; #define PG8_WAIT_V(n) asm volatile("s_waitcnt vmcnt(" #n ")" ::: "memory")
; #define PG8_WAIT_L(n) asm volatile("s_waitcnt lgkmcnt(" #n ")" ::: "memory")
; #define PG8_BAR __builtin_amdgcn_s_barrier()
; #define PG8_SCHED __builtin_amdgcn_sched_barrier(0)
; template <class Epi, class Sched, bool ALIGN_EPI = false, bool SP2 = false, bool DUAL = false>
; __device__ __forceinline__ void gemm_phase(PG8_LAS unsigned char* lds, const Gemm g, const Sched& S, const Epi& E) {
;     ...
;             PG8_LDB(B0, 0, 0); PG8_LDB(B1, 0, 1); PG8_SCHED; PG8_LDA(At, 0, 0); PG8_STAGE(PG8_SA(1, 1), a1 + hstep, voffA);
;             PG8_WAIT_V(8); PG8_WAIT_L(0); PG8_BAR; PG8_MMA(0, 0, At, B0); PG8_MMA(0, 1, At, B1); PG8_BAR; PG8_SCHED;
;             PG8_LDA(At, 0, 1); PG8_STAGE(PG8_SB(0, 0), b2, voffB); PG8_STAGE(PG8_SB(0, 1), b2 + hstep, voffB); PG8_STAGE(PG8_SA(0, 0), a2, voffA);
;             PG8_WAIT_V(8); PG8_WAIT_L(0); PG8_BAR; PG8_MMA(1, 0, At, B0); PG8_MMA(1, 1, At, B1); PG8_BAR; PG8_SCHED;
.LBB0_992:
	ds_read_b128 v[128:131], v215
	ds_read_b128 v[132:135], v215 offset:1024
	ds_read_b128 v[136:139], v215 offset:2048
	ds_read_b128 v[140:143], v215 offset:3072
	ds_read_b128 v[144:147], v216
	ds_read_b128 v[148:151], v216 offset:1024
	ds_read_b128 v[152:155], v216 offset:2048
	ds_read_b128 v[156:159], v216 offset:3072
	s_add_u32 s14, s40, 0xfff80080
	s_addc_u32 s15, s41, -1
	s_cmp_eq_u32 s65, 28
	s_cselect_b32 s27, s25, s15
	s_cselect_b32 s26, s28, s14
	s_cselect_b32 s15, s23, s64
	s_cselect_b32 s14, s29, s63
	v_lshl_add_u64 v[228:229], s[40:41], 0, v[180:181]
	s_add_i32 m0, s39, 0xc000
	ds_read_b128 v[160:163], v217
	ds_read_b128 v[164:167], v217 offset:1024
	ds_read_b128 v[188:191], v217 offset:2048
	ds_read_b128 v[192:195], v217 offset:3072
	ds_read_b128 v[196:199], v217 offset:4096
	ds_read_b128 v[202:205], v217 offset:5120
	ds_read_b128 v[206:209], v217 offset:6144
	ds_read_b128 v[220:223], v217 offset:7168
	global_load_lds_dwordx4 v[228:229], off
	v_lshl_add_u64 v[228:229], s[40:41], 0, v[182:183]
	s_add_i32 m0, s39, 0xe000
	s_nop 0
	global_load_lds_dwordx4 v[228:229], off
	s_waitcnt vmcnt(8)
	s_waitcnt lgkmcnt(0)
	s_setprio 1
	s_barrier
	v_mfma_f32_16x16x32_bf16 v[124:127], v[128:131], v[160:163], v[124:127]
	v_mfma_f32_16x16x32_bf16 v[120:123], v[136:139], v[160:163], v[120:123]
	v_mfma_f32_16x16x32_bf16 v[108:111], v[128:131], v[188:191], v[108:111]
	v_mfma_f32_16x16x32_bf16 v[104:107], v[136:139], v[188:191], v[104:107]
	v_mfma_f32_16x16x32_bf16 v[92:95], v[128:131], v[196:199], v[92:95]
	v_mfma_f32_16x16x32_bf16 v[88:91], v[136:139], v[196:199], v[88:91]
	v_mfma_f32_16x16x32_bf16 v[76:79], v[128:131], v[206:209], v[76:79]
	v_mfma_f32_16x16x32_bf16 v[72:75], v[136:139], v[206:209], v[72:75]
	v_mfma_f32_16x16x32_bf16 v[124:127], v[132:135], v[164:167], v[124:127]
	v_mfma_f32_16x16x32_bf16 v[120:123], v[140:143], v[164:167], v[120:123]
	v_mfma_f32_16x16x32_bf16 v[108:111], v[132:135], v[192:195], v[108:111]
	v_mfma_f32_16x16x32_bf16 v[104:107], v[140:143], v[192:195], v[104:107]
	v_mfma_f32_16x16x32_bf16 v[92:95], v[132:135], v[202:205], v[92:95]
	v_mfma_f32_16x16x32_bf16 v[88:91], v[140:143], v[202:205], v[88:91]
	v_mfma_f32_16x16x32_bf16 v[76:79], v[132:135], v[220:223], v[76:79]
	v_mfma_f32_16x16x32_bf16 v[72:75], v[140:143], v[220:223], v[72:75]
	s_setprio 0
	s_setprio 1
	v_mfma_f32_16x16x32_bf16 v[116:119], v[144:147], v[160:163], v[116:119]
	v_mfma_f32_16x16x32_bf16 v[112:115], v[152:155], v[160:163], v[112:115]
	v_mfma_f32_16x16x32_bf16 v[100:103], v[144:147], v[188:191], v[100:103]
	v_mfma_f32_16x16x32_bf16 v[96:99], v[152:155], v[188:191], v[96:99]
	v_mfma_f32_16x16x32_bf16 v[84:87], v[144:147], v[196:199], v[84:87]
	v_mfma_f32_16x16x32_bf16 v[80:83], v[152:155], v[196:199], v[80:83]
	v_mfma_f32_16x16x32_bf16 v[68:71], v[144:147], v[206:209], v[68:71]
	v_mfma_f32_16x16x32_bf16 v[64:67], v[152:155], v[206:209], v[64:67]
	v_mfma_f32_16x16x32_bf16 v[116:119], v[148:151], v[164:167], v[116:119]
	v_mfma_f32_16x16x32_bf16 v[112:115], v[156:159], v[164:167], v[112:115]
	v_mfma_f32_16x16x32_bf16 v[100:103], v[148:151], v[192:195], v[100:103]
	v_mfma_f32_16x16x32_bf16 v[96:99], v[156:159], v[192:195], v[96:99]
	v_mfma_f32_16x16x32_bf16 v[84:87], v[148:151], v[202:205], v[84:87]
	v_mfma_f32_16x16x32_bf16 v[80:83], v[156:159], v[202:205], v[80:83]
	v_mfma_f32_16x16x32_bf16 v[68:71], v[148:151], v[220:223], v[68:71]
	v_mfma_f32_16x16x32_bf16 v[64:67], v[156:159], v[220:223], v[64:67]
	s_barrier
	s_setprio 0
	s_add_i32 s66, s50, s34
	v_lshl_add_u64 v[228:229], s[14:15], 0, v[170:171]
	s_mov_b32 m0, s66
	ds_read_b128 v[160:163], v217 offset:16384
	ds_read_b128 v[164:167], v217 offset:17408
	ds_read_b128 v[188:191], v217 offset:18432
	ds_read_b128 v[192:195], v217 offset:19456
	ds_read_b128 v[196:199], v217 offset:20480
	ds_read_b128 v[202:205], v217 offset:21504
	ds_read_b128 v[206:209], v217 offset:22528
	ds_read_b128 v[220:223], v217 offset:23552
	global_load_lds_dwordx4 v[228:229], off
	s_add_i32 m0, s66, 0x2000
	s_add_u32 s66, s14, 0x80000
	v_lshl_add_u64 v[232:233], s[14:15], 0, v[174:175]
	s_addc_u32 s67, s15, 0
	s_add_i32 s68, s51, s34
	global_load_lds_dwordx4 v[232:233], off
	v_lshl_add_u64 v[234:235], s[66:67], 0, v[170:171]
	s_mov_b32 m0, s68
	v_lshl_add_u64 v[236:237], s[26:27], 0, v[172:173]
	global_load_lds_dwordx4 v[234:235], off
	v_lshl_add_u64 v[234:235], s[66:67], 0, v[174:175]
	s_add_i32 m0, s68, 0x2000
	s_nop 0
	global_load_lds_dwordx4 v[234:235], off
	v_lshl_add_u64 v[234:235], s[26:27], 0, v[168:169]
	s_mov_b32 m0, s39
	s_nop 0
	global_load_lds_dwordx4 v[234:235], off
	s_mov_b32 m0, s42
	s_nop 0
	global_load_lds_dwordx4 v[236:237], off
	s_waitcnt vmcnt(8)
	s_waitcnt lgkmcnt(0)
	s_setprio 1
	s_barrier
; #define PG8_STAGE(bufoff, gbase, voff) do { _Pragma("unroll") for (int _i = 0; _i < 2; ++_i) \
;         __builtin_amdgcn_global_load_lds((const unsigned*)((const char*)(gbase) + (voff)[_i]), (PG8_LAS unsigned*)(lds + (bufoff) + ldsw + _i * 8192), 16, 0, 0); } while (0)
; #define PG8_LDA(dst, b, h) do { _Pragma("unroll") for (int m = 0; m < 4; ++m) _Pragma("unroll") for (int k = 0; k < 2; ++k) dst[m][k] = *(const PG8_LAS bf16x8*)(lds + PG8_SA(b, h) + aoff + m * 2048 + k * 1024); } while (0)
; #define PG8_LDB(dst, b, h) do { _Pragma("unroll") for (int n = 0; n < 2; ++n) _Pragma("unroll") for (int k = 0; k < 2; ++k) dst[n][k] = *(const PG8_LAS bf16x8*)(lds + PG8_SB(b, h) + boff + n * 2048 + k * 1024); } while (0)
; #define PG8_MMA(ai, bj, At, Bt) do { __builtin_amdgcn_s_setprio(1); _Pragma("unroll") for (int m = 0; m < 4; ++m) _Pragma("unroll") for (int n = 0; n < 2; ++n) _Pragma("unroll") for (int k = 0; k < 2; ++k) \
;         acc[ai][bj][m][n] = __builtin_amdgcn_mfma_f32_16x16x32_bf16(Bt[n][k], At[m][k], acc[ai][bj][m][n], 0, 0, 0); __builtin_amdgcn_s_setprio(0); } while (0)
; #define PG8_WAIT_V(n) asm volatile("s_waitcnt vmcnt(" #n ")" ::: "memory")
; #define PG8_WAIT_L(n) asm volatile("s_waitcnt lgkmcnt(" #n ")" ::: "memory")
; #define PG8_BAR __builtin_amdgcn_s_barrier()
; #define PG8_SCHED __builtin_amdgcn_sched_barrier(0)
; template <class Epi, class Sched, bool ALIGN_EPI = false, bool SP2 = false, bool DUAL = false>
; __device__ __forceinline__ void gemm_phase(PG8_LAS unsigned char* lds, const Gemm g, const Sched& S, const Epi& E) {
;     ...
;             PG8_WAIT_V(8); PG8_WAIT_L(0); PG8_BAR; PG8_MMA(1, 0, At, B0); PG8_MMA(1, 1, At, B1); PG8_BAR; PG8_SCHED;
;             PG8_LDB(B0, 1, 0); PG8_LDB(B1, 1, 1); PG8_SCHED; PG8_LDA(At, 1, 0); PG8_STAGE(PG8_SA(0, 1), a2 + hstep, voffA);
;             PG8_WAIT_V(8); PG8_WAIT_L(0); PG8_BAR; PG8_MMA(0, 0, At, B0); PG8_MMA(0, 1, At, B1); PG8_BAR; PG8_SCHED;
	v_mfma_f32_16x16x32_bf16 v[60:63], v[128:131], v[160:163], v[60:63]
	v_mfma_f32_16x16x32_bf16 v[56:59], v[136:139], v[160:163], v[56:59]
	v_mfma_f32_16x16x32_bf16 v[44:47], v[128:131], v[188:191], v[44:47]
	v_mfma_f32_16x16x32_bf16 v[40:43], v[136:139], v[188:191], v[40:43]
	v_mfma_f32_16x16x32_bf16 v[28:31], v[128:131], v[196:199], v[28:31]
	v_mfma_f32_16x16x32_bf16 v[24:27], v[136:139], v[196:199], v[24:27]
	v_mfma_f32_16x16x32_bf16 v[12:15], v[128:131], v[206:209], v[12:15]
	v_mfma_f32_16x16x32_bf16 v[8:11], v[136:139], v[206:209], v[8:11]
	v_mfma_f32_16x16x32_bf16 v[60:63], v[132:135], v[164:167], v[60:63]
	v_mfma_f32_16x16x32_bf16 v[56:59], v[140:143], v[164:167], v[56:59]
	v_mfma_f32_16x16x32_bf16 v[44:47], v[132:135], v[192:195], v[44:47]
	v_mfma_f32_16x16x32_bf16 v[40:43], v[140:143], v[192:195], v[40:43]
	v_mfma_f32_16x16x32_bf16 v[28:31], v[132:135], v[202:205], v[28:31]
	v_mfma_f32_16x16x32_bf16 v[24:27], v[140:143], v[202:205], v[24:27]
	v_mfma_f32_16x16x32_bf16 v[12:15], v[132:135], v[220:223], v[12:15]
	v_mfma_f32_16x16x32_bf16 v[8:11], v[140:143], v[220:223], v[8:11]
	s_setprio 0
	s_setprio 1
	v_mfma_f32_16x16x32_bf16 v[52:55], v[144:147], v[160:163], v[52:55]
	v_mfma_f32_16x16x32_bf16 v[48:51], v[152:155], v[160:163], v[48:51]
	v_mfma_f32_16x16x32_bf16 v[36:39], v[144:147], v[188:191], v[36:39]
	v_mfma_f32_16x16x32_bf16 v[32:35], v[152:155], v[188:191], v[32:35]
	v_mfma_f32_16x16x32_bf16 v[20:23], v[144:147], v[196:199], v[20:23]
	v_mfma_f32_16x16x32_bf16 v[16:19], v[152:155], v[196:199], v[16:19]
	v_mfma_f32_16x16x32_bf16 v[4:7], v[144:147], v[206:209], v[4:7]
	v_mfma_f32_16x16x32_bf16 v[0:3], v[152:155], v[206:209], v[0:3]
	v_mfma_f32_16x16x32_bf16 v[52:55], v[148:151], v[164:167], v[52:55]
	v_mfma_f32_16x16x32_bf16 v[48:51], v[156:159], v[164:167], v[48:51]
	v_mfma_f32_16x16x32_bf16 v[36:39], v[148:151], v[192:195], v[36:39]
	v_mfma_f32_16x16x32_bf16 v[32:35], v[156:159], v[192:195], v[32:35]
	v_mfma_f32_16x16x32_bf16 v[20:23], v[148:151], v[202:205], v[20:23]
	v_mfma_f32_16x16x32_bf16 v[16:19], v[156:159], v[202:205], v[16:19]
	v_mfma_f32_16x16x32_bf16 v[4:7], v[148:151], v[220:223], v[4:7]
	v_mfma_f32_16x16x32_bf16 v[0:3], v[156:159], v[220:223], v[0:3]
	s_barrier
	s_setprio 0
	s_add_i32 s66, 0, 0x18000
	s_add_i32 s67, 0, 0x1c000
	v_add_u32_e32 v140, s66, v213
	v_add_u32_e32 v156, s67, v213
	ds_read_b128 v[128:131], v140
	ds_read_b128 v[132:135], v140 offset:1024
	ds_read_b128 v[136:139], v140 offset:2048
	ds_read_b128 v[140:143], v140 offset:3072
	ds_read_b128 v[144:147], v156
	ds_read_b128 v[148:151], v156 offset:1024
	ds_read_b128 v[152:155], v156 offset:2048
	ds_read_b128 v[156:159], v156 offset:3072
	s_add_u32 s26, s26, 0x80000
	s_addc_u32 s27, s27, 0
	s_mov_b32 m0, s43
	v_lshl_add_u64 v[238:239], s[26:27], 0, v[168:169]
	ds_read_b128 v[160:163], v217 offset:32768
	ds_read_b128 v[164:167], v217 offset:33792
	ds_read_b128 v[188:191], v217 offset:34816
	ds_read_b128 v[192:195], v217 offset:35840
	ds_read_b128 v[196:199], v217 offset:36864
	ds_read_b128 v[202:205], v217 offset:37888
	ds_read_b128 v[206:209], v217 offset:38912
	ds_read_b128 v[220:223], v217 offset:39936
	global_load_lds_dwordx4 v[238:239], off
	v_lshl_add_u64 v[238:239], s[26:27], 0, v[172:173]
	s_mov_b32 m0, s44
	s_nop 0
	global_load_lds_dwordx4 v[238:239], off
	s_waitcnt vmcnt(8)
	s_waitcnt lgkmcnt(0)
	s_setprio 1
	s_barrier
	v_mfma_f32_16x16x32_bf16 v[124:127], v[128:131], v[160:163], v[124:127]
	v_mfma_f32_16x16x32_bf16 v[120:123], v[136:139], v[160:163], v[120:123]
	v_mfma_f32_16x16x32_bf16 v[108:111], v[128:131], v[188:191], v[108:111]
	v_mfma_f32_16x16x32_bf16 v[104:107], v[136:139], v[188:191], v[104:107]
	v_mfma_f32_16x16x32_bf16 v[92:95], v[128:131], v[196:199], v[92:95]
	v_mfma_f32_16x16x32_bf16 v[88:91], v[136:139], v[196:199], v[88:91]
	v_mfma_f32_16x16x32_bf16 v[76:79], v[128:131], v[206:209], v[76:79]
	v_mfma_f32_16x16x32_bf16 v[72:75], v[136:139], v[206:209], v[72:75]
	v_mfma_f32_16x16x32_bf16 v[124:127], v[132:135], v[164:167], v[124:127]
	v_mfma_f32_16x16x32_bf16 v[120:123], v[140:143], v[164:167], v[120:123]
	v_mfma_f32_16x16x32_bf16 v[108:111], v[132:135], v[192:195], v[108:111]
	v_mfma_f32_16x16x32_bf16 v[104:107], v[140:143], v[192:195], v[104:107]
	v_mfma_f32_16x16x32_bf16 v[92:95], v[132:135], v[202:205], v[92:95]
	v_mfma_f32_16x16x32_bf16 v[88:91], v[140:143], v[202:205], v[88:91]
	v_mfma_f32_16x16x32_bf16 v[76:79], v[132:135], v[220:223], v[76:79]
	v_mfma_f32_16x16x32_bf16 v[72:75], v[140:143], v[220:223], v[72:75]
	s_setprio 0
	s_setprio 1
	v_mfma_f32_16x16x32_bf16 v[116:119], v[144:147], v[160:163], v[116:119]
	v_mfma_f32_16x16x32_bf16 v[112:115], v[152:155], v[160:163], v[112:115]
	v_mfma_f32_16x16x32_bf16 v[100:103], v[144:147], v[188:191], v[100:103]
	v_mfma_f32_16x16x32_bf16 v[96:99], v[152:155], v[188:191], v[96:99]
	v_mfma_f32_16x16x32_bf16 v[84:87], v[144:147], v[196:199], v[84:87]
	v_mfma_f32_16x16x32_bf16 v[80:83], v[152:155], v[196:199], v[80:83]
	v_mfma_f32_16x16x32_bf16 v[68:71], v[144:147], v[206:209], v[68:71]
	v_mfma_f32_16x16x32_bf16 v[64:67], v[152:155], v[206:209], v[64:67]
	v_mfma_f32_16x16x32_bf16 v[116:119], v[148:151], v[164:167], v[116:119]
	v_mfma_f32_16x16x32_bf16 v[112:115], v[156:159], v[164:167], v[112:115]
	v_mfma_f32_16x16x32_bf16 v[100:103], v[148:151], v[192:195], v[100:103]
	v_mfma_f32_16x16x32_bf16 v[96:99], v[156:159], v[192:195], v[96:99]
	v_mfma_f32_16x16x32_bf16 v[84:87], v[148:151], v[202:205], v[84:87]
	v_mfma_f32_16x16x32_bf16 v[80:83], v[156:159], v[202:205], v[80:83]
	v_mfma_f32_16x16x32_bf16 v[68:71], v[148:151], v[220:223], v[68:71]
	v_mfma_f32_16x16x32_bf16 v[64:67], v[156:159], v[220:223], v[64:67]
	s_barrier
; #define PG8_STAGE(bufoff, gbase, voff) do { _Pragma("unroll") for (int _i = 0; _i < 2; ++_i) \
;         __builtin_amdgcn_global_load_lds((const unsigned*)((const char*)(gbase) + (voff)[_i]), (PG8_LAS unsigned*)(lds + (bufoff) + ldsw + _i * 8192), 16, 0, 0); } while (0)
; #define PG8_LDA(dst, b, h) do { _Pragma("unroll") for (int m = 0; m < 4; ++m) _Pragma("unroll") for (int k = 0; k < 2; ++k) dst[m][k] = *(const PG8_LAS bf16x8*)(lds + PG8_SA(b, h) + aoff + m * 2048 + k * 1024); } while (0)
; #define PG8_MMA(ai, bj, At, Bt) do { __builtin_amdgcn_s_setprio(1); _Pragma("unroll") for (int m = 0; m < 4; ++m) _Pragma("unroll") for (int n = 0; n < 2; ++n) _Pragma("unroll") for (int k = 0; k < 2; ++k) \
;         acc[ai][bj][m][n] = __builtin_amdgcn_mfma_f32_16x16x32_bf16(Bt[n][k], At[m][k], acc[ai][bj][m][n], 0, 0, 0); __builtin_amdgcn_s_setprio(0); } while (0)
; #define PG8_WAIT_V(n) asm volatile("s_waitcnt vmcnt(" #n ")" ::: "memory")
; #define PG8_WAIT_L(n) asm volatile("s_waitcnt lgkmcnt(" #n ")" ::: "memory")
; #define PG8_BAR __builtin_amdgcn_s_barrier()
; #define PG8_SCHED __builtin_amdgcn_sched_barrier(0)
; template <class Epi, class Sched, bool ALIGN_EPI = false, bool SP2 = false, bool DUAL = false>
; __device__ __forceinline__ void gemm_phase(PG8_LAS unsigned char* lds, const Gemm g, const Sched& S, const Epi& E) {
;     ...
;             PG8_LDA(At, 1, 1); PG8_STAGE(PG8_SB(1, 0), b3, voffB); PG8_STAGE(PG8_SB(1, 1), b3 + hstep, voffB); PG8_STAGE(PG8_SA(1, 0), a3, voffA);
;             PG8_WAIT_V(8); PG8_WAIT_L(0); PG8_BAR; PG8_MMA(1, 0, At, B0); PG8_MMA(1, 1, At, B1); PG8_BAR; PG8_SCHED;
;     __device__ __forceinline__ void operator()(const f32x4 (&acc)[2][2][4][2], const Unit& u, int wr, int wc, int fr, int fq) const {
;         const int rowb = u.pm * BM + wr * 64 + fr, col = u.pn * HALF + wc * 32 + fq * 8;
;         f32x4 p[2][4][2];
; #pragma unroll
;         for (int ai = 0; ai < 2; ++ai)
; #pragma unroll
;             for (int m = 0; m < 4; ++m) { const float* sp = ss2 + (size_t)(rowb + ai * HALF + m * 16) * 32 + fq * 8; p[ai][m][0] = *(const f32x4*)sp; p[ai][m][1] = *(const f32x4*)(sp + 4); }
	s_setprio 0
	s_add_i32 s26, s66, s34
	v_lshl_add_u64 v[228:229], v[228:229], 0, s[12:13]
	s_mov_b32 m0, s26
	ds_read_b128 v[160:163], v217 offset:49152
	ds_read_b128 v[164:167], v217 offset:50176
	ds_read_b128 v[188:191], v217 offset:51200
	ds_read_b128 v[192:195], v217 offset:52224
	ds_read_b128 v[196:199], v217 offset:53248
	ds_read_b128 v[202:205], v217 offset:54272
	ds_read_b128 v[206:209], v217 offset:55296
	ds_read_b128 v[220:223], v217 offset:56320
	global_load_lds_dwordx4 v[228:229], off
	s_add_i32 m0, s26, 0x2000
	s_add_u32 s14, s14, 0x80080
	v_lshl_add_u64 v[228:229], v[232:233], 0, s[12:13]
	s_addc_u32 s15, s15, 0
	s_add_i32 s26, s67, s34
	global_load_lds_dwordx4 v[228:229], off
	v_lshl_add_u64 v[228:229], s[14:15], 0, v[170:171]
	s_mov_b32 m0, s26
	s_nop 0
	global_load_lds_dwordx4 v[228:229], off
	v_lshl_add_u64 v[228:229], s[14:15], 0, v[174:175]
	s_add_i32 m0, s26, 0x2000
	s_nop 0
	global_load_lds_dwordx4 v[228:229], off
	v_lshl_add_u64 v[228:229], v[234:235], 0, s[12:13]
	s_mov_b32 m0, s47
	s_nop 0
	global_load_lds_dwordx4 v[228:229], off
	v_lshl_add_u64 v[228:229], v[236:237], 0, s[12:13]
	s_mov_b32 m0, s48
	s_nop 0
	global_load_lds_dwordx4 v[228:229], off
	s_waitcnt vmcnt(8)
	s_waitcnt lgkmcnt(0)
	s_setprio 1
	s_barrier
	v_mfma_f32_16x16x32_bf16 v[60:63], v[128:131], v[160:163], v[60:63]
	v_mfma_f32_16x16x32_bf16 v[56:59], v[136:139], v[160:163], v[56:59]
	v_mfma_f32_16x16x32_bf16 v[44:47], v[128:131], v[188:191], v[44:47]
	v_mfma_f32_16x16x32_bf16 v[40:43], v[136:139], v[188:191], v[40:43]
	v_mfma_f32_16x16x32_bf16 v[28:31], v[128:131], v[196:199], v[28:31]
	v_mfma_f32_16x16x32_bf16 v[24:27], v[136:139], v[196:199], v[24:27]
	v_mfma_f32_16x16x32_bf16 v[12:15], v[128:131], v[206:209], v[12:15]
	v_mfma_f32_16x16x32_bf16 v[8:11], v[136:139], v[206:209], v[8:11]
	v_mfma_f32_16x16x32_bf16 v[60:63], v[132:135], v[164:167], v[60:63]
	v_mfma_f32_16x16x32_bf16 v[56:59], v[140:143], v[164:167], v[56:59]
	v_mfma_f32_16x16x32_bf16 v[44:47], v[132:135], v[192:195], v[44:47]
	v_mfma_f32_16x16x32_bf16 v[40:43], v[140:143], v[192:195], v[40:43]
	v_mfma_f32_16x16x32_bf16 v[28:31], v[132:135], v[202:205], v[28:31]
	v_mfma_f32_16x16x32_bf16 v[24:27], v[140:143], v[202:205], v[24:27]
	v_mfma_f32_16x16x32_bf16 v[12:15], v[132:135], v[220:223], v[12:15]
	v_mfma_f32_16x16x32_bf16 v[8:11], v[140:143], v[220:223], v[8:11]
	s_setprio 0
	s_setprio 1
	v_mfma_f32_16x16x32_bf16 v[52:55], v[144:147], v[160:163], v[52:55]
	v_mfma_f32_16x16x32_bf16 v[48:51], v[152:155], v[160:163], v[48:51]
	v_mfma_f32_16x16x32_bf16 v[36:39], v[144:147], v[188:191], v[36:39]
	v_mfma_f32_16x16x32_bf16 v[32:35], v[152:155], v[188:191], v[32:35]
	v_mfma_f32_16x16x32_bf16 v[20:23], v[144:147], v[196:199], v[20:23]
	v_mfma_f32_16x16x32_bf16 v[16:19], v[152:155], v[196:199], v[16:19]
	v_mfma_f32_16x16x32_bf16 v[4:7], v[144:147], v[206:209], v[4:7]
	v_mfma_f32_16x16x32_bf16 v[0:3], v[152:155], v[206:209], v[0:3]
	v_mfma_f32_16x16x32_bf16 v[52:55], v[148:151], v[164:167], v[52:55]
	v_mfma_f32_16x16x32_bf16 v[48:51], v[156:159], v[164:167], v[48:51]
	v_mfma_f32_16x16x32_bf16 v[36:39], v[148:151], v[192:195], v[36:39]
	v_mfma_f32_16x16x32_bf16 v[32:35], v[156:159], v[192:195], v[32:35]
	v_mfma_f32_16x16x32_bf16 v[20:23], v[148:151], v[202:205], v[20:23]
	v_mfma_f32_16x16x32_bf16 v[16:19], v[156:159], v[202:205], v[16:19]
	v_mfma_f32_16x16x32_bf16 v[4:7], v[148:151], v[220:223], v[4:7]
	v_mfma_f32_16x16x32_bf16 v[0:3], v[156:159], v[220:223], v[0:3]
	s_barrier
	s_setprio 0
	s_add_i32 s65, s65, 2
	s_add_u32 s40, s40, 0x100
	s_addc_u32 s41, s41, 0
	s_add_u32 s63, s63, 0x100
	s_addc_u32 s64, s64, 0
	s_cmp_gt_u32 s65, 29
	s_cbranch_scc0 .LBB0_992
	v_lshl_add_u32 v144, s38, 8, v212
	v_ashrrev_i32_e32 v145, 31, v144
	v_or_b32_e32 v206, 16, v144
	v_lshlrev_b64 v[128:129], 7, v[144:145]
	v_ashrrev_i32_e32 v207, 31, v206
	v_lshl_add_u64 v[132:133], v[178:179], 0, v[128:129]
	v_lshlrev_b64 v[136:137], 7, v[206:207]
	global_load_dwordx4 v[128:131], v[132:133], off
	s_nop 0
	global_load_dwordx4 v[132:135], v[132:133], off offset:16
	v_lshl_add_u64 v[140:141], v[178:179], 0, v[136:137]
	global_load_dwordx4 v[136:139], v[140:141], off
	s_nop 0
	global_load_dwordx4 v[140:143], v[140:141], off offset:16
	v_readlane_b32 s64, v254, 20
	v_readlane_b32 s70, v254, 26
	v_readlane_b32 s71, v254, 27
	v_readlane_b32 s72, v254, 28
	v_readlane_b32 s73, v254, 29
	v_readlane_b32 s74, v254, 30
	v_readlane_b32 s75, v254, 31
	v_readlane_b32 s76, v254, 32
	v_readlane_b32 s77, v254, 33
	s_and_b64 vcc, exec, s[16:17]
	s_mov_b64 s[70:71], s[74:75]
	s_mov_b64 s[72:73], s[76:77]
	v_readlane_b32 s65, v254, 21
	v_readlane_b32 s66, v254, 22
	v_readlane_b32 s67, v254, 23
	v_readlane_b32 s68, v254, 24
	v_readlane_b32 s69, v254, 25
	v_readlane_b32 s78, v254, 34
	v_readlane_b32 s79, v254, 35
	s_cbranch_vccz .LBB0_995
	s_barrier
; __device__ __forceinline__ u32x4 pk8(const f32x4 a, const f32x4 b) { u32x4 w; w.x = pk_bf16(a[0], a[1]); w.y = pk_bf16(a[2], a[3]); w.z = pk_bf16(b[0], b[1]); w.w = pk_bf16(b[2], b[3]); return w; }
; __device__ __forceinline__ float hsum4(const f32x4 v) { return (v[0] + v[1]) + (v[2] + v[3]); }
; __device__ __forceinline__ float fast_sigmoid(float x) { return __builtin_amdgcn_rcpf(1.0f + __expf(-x)); }
;     __device__ __forceinline__ void operator()(const f32x4 (&acc)[2][2][4][2], const Unit& u, int wr, int wc, int fr, int fq) const {
;         const int rowb = u.pm * BM + wr * 64 + fr, col = u.pn * HALF + wc * 32 + fq * 8;
;         f32x4 p[2][4][2];
; #pragma unroll
;         for (int ai = 0; ai < 2; ++ai)
; #pragma unroll
;             for (int m = 0; m < 4; ++m) { const float* sp = ss2 + (size_t)(rowb + ai * HALF + m * 16) * 32 + fq * 8; p[ai][m][0] = *(const f32x4*)sp; p[ai][m][1] = *(const f32x4*)(sp + 4); }
; #pragma unroll
;         for (int ai = 0; ai < 2; ++ai)
; #pragma unroll
;             for (int m = 0; m < 4; ++m) {
;                 const int row = rowb + ai * HALF + m * 16;
;                 float s = hsum4(p[ai][m][0]) + hsum4(p[ai][m][1]);
;                 s += __shfl_xor(s, 16); s += __shfl_xor(s, 32);
;                 const float rs = rsqrtf(s * (1.0f / DM) + EPS);
;                 f32x4 h[2];
; #pragma unroll
;                 for (int n = 0; n < 2; ++n)
; #pragma unroll
;                     for (int e = 0; e < 4; ++e) { const float a = acc[ai][0][m][n][e] * rs, b = acc[ai][1][m][n][e] * rs; h[n][e] = a * fast_sigmoid(a) * b; }
;                 __builtin_nontemporal_store(pk8(h[0], h[1]), (u32x4*)(H + (size_t)row * DFF + col));
.LBB0_995:
	v_and_b32_e32 v145, 64, v218
	v_xor_b32_e32 v148, 16, v218
	v_add_u32_e32 v150, 64, v145
	v_lshl_or_b32 v146, s62, 7, v214
	v_xor_b32_e32 v149, 32, v218
	v_or_b32_e32 v208, 32, v144
	v_or_b32_e32 v204, 48, v144
	v_add_u32_e32 v202, 0x80, v144
	v_cmp_lt_i32_e32 vcc, v148, v150
	v_mov_b64_e32 v[188:189], s[10:11]
	v_ashrrev_i32_e32 v147, 31, v146
	v_ashrrev_i32_e32 v209, 31, v208
	v_ashrrev_i32_e32 v205, 31, v204
	v_ashrrev_i32_e32 v203, 31, v202
	v_cndmask_b32_e32 v158, v218, v148, vcc
	v_cmp_lt_i32_e32 vcc, v149, v150
	v_add_u32_e32 v198, 0x90, v144
	v_add_u32_e32 v194, 0xa0, v144
	v_add_u32_e32 v190, 0xb0, v144
	v_mad_i64_i32 v[144:145], s[14:15], v144, s60, v[188:189]
	v_cndmask_b32_e32 v159, v218, v149, vcc
	v_lshlrev_b64 v[192:193], 1, v[146:147]
	v_lshlrev_b64 v[146:147], 7, v[208:209]
	v_lshlrev_b64 v[148:149], 7, v[204:205]
	v_lshlrev_b64 v[150:151], 7, v[202:203]
	v_lshl_add_u64 v[228:229], v[144:145], 0, v[192:193]
	v_lshl_add_u64 v[144:145], v[178:179], 0, v[146:147]
	v_lshl_add_u64 v[146:147], v[178:179], 0, v[148:149]
	v_lshl_add_u64 v[148:149], v[178:179], 0, v[150:151]
	v_ashrrev_i32_e32 v195, 31, v194
	v_lshlrev_b64 v[154:155], 7, v[194:195]
	v_lshlrev_b32_e32 v195, 2, v158
	v_ashrrev_i32_e32 v191, 31, v190
	v_lshlrev_b64 v[156:157], 7, v[190:191]
	v_lshlrev_b32_e32 v191, 2, v159
	global_load_dwordx4 v[220:223], v[144:145], off
	global_load_dwordx4 v[232:235], v[144:145], off offset:16
	global_load_dwordx4 v[164:167], v[146:147], off
	global_load_dwordx4 v[160:163], v[146:147], off offset:16
	v_ashrrev_i32_e32 v199, 31, v198
	v_lshlrev_b64 v[152:153], 7, v[198:199]
	v_mov_b64_e32 v[196:197], s[20:21]
	v_lshl_add_u64 v[236:237], v[178:179], 0, v[152:153]
	v_lshl_add_u64 v[238:239], v[178:179], 0, v[154:155]
	v_lshl_add_u64 v[240:241], v[178:179], 0, v[156:157]
	s_waitcnt vmcnt(4)
	v_mov_b32_e32 v150, v128
	v_mov_b32_e32 v151, v132
	v_mov_b32_e32 v132, v129
	v_mov_b32_e32 v128, v130
	v_mov_b32_e32 v129, v134
	v_mov_b32_e32 v134, v131
	v_pk_add_f32 v[130:131], v[150:151], v[132:133]
	v_pk_add_f32 v[128:129], v[128:129], v[134:135]
	v_mov_b32_e32 v132, v136
	v_mov_b32_e32 v133, v140
	v_mov_b32_e32 v140, v137
	v_mov_b32_e32 v134, v138
	v_mov_b32_e32 v135, v142
	v_mov_b32_e32 v142, v139
	v_pk_add_f32 v[128:129], v[130:131], v[128:129]
	v_pk_add_f32 v[130:131], v[132:133], v[140:141]
	v_pk_add_f32 v[132:133], v[134:135], v[142:143]
	global_load_dwordx4 v[156:159], v[148:149], off
	global_load_dwordx4 v[152:155], v[148:149], off offset:16
	s_nop 0
	global_load_dwordx4 v[148:151], v[236:237], off
	global_load_dwordx4 v[144:147], v[236:237], off offset:16
	v_pk_add_f32 v[130:131], v[130:131], v[132:133]
	v_mov_b32_e32 v133, v128
	v_mov_b32_e32 v132, v130
	v_mov_b32_e32 v128, v131
	v_pk_add_f32 v[128:129], v[132:133], v[128:129]
	ds_bpermute_b32 v131, v195, v129
	ds_bpermute_b32 v130, v195, v128
	s_waitcnt lgkmcnt(0)
	v_pk_add_f32 v[128:129], v[128:129], v[130:131]
	ds_bpermute_b32 v131, v191, v129
	ds_bpermute_b32 v130, v191, v128
	s_waitcnt lgkmcnt(0)
	v_pk_add_f32 v[128:129], v[128:129], v[130:131]
	s_nop 0
	v_pk_fma_f32 v[236:237], v[128:129], s[18:19], v[196:197] op_sel_hi:[1,0,0]
	s_nop 0
	v_mul_f32_e32 v128, 0x4b800000, v237
	v_cmp_gt_f32_e32 vcc, s61, v237
	s_nop 1
	v_cndmask_b32_e32 v128, v237, v128, vcc
	v_rsq_f32_e32 v199, v128
	global_load_dwordx4 v[140:143], v[238:239], off
	global_load_dwordx4 v[136:139], v[238:239], off offset:16
	global_load_dwordx4 v[132:135], v[240:241], off
	global_load_dwordx4 v[128:131], v[240:241], off offset:16
	v_mul_f32_e32 v203, 0x45800000, v199
	v_cndmask_b32_e32 v238, v199, v203, vcc
	v_pk_mul_f32 v[124:125], v[124:125], v[238:239] op_sel_hi:[1,0]
	v_pk_mul_f32 v[126:127], v[126:127], v[238:239] op_sel_hi:[1,0]
	v_mul_f32_e32 v199, 0xbfb8aa3b, v124
	v_mul_f32_e32 v203, 0xbfb8aa3b, v125
	v_mul_f32_e32 v205, 0xbfb8aa3b, v126
	v_mul_f32_e32 v207, 0xbfb8aa3b, v127
	v_exp_f32_e32 v199, v199
	v_exp_f32_e32 v203, v203
	v_exp_f32_e32 v205, v205
	v_exp_f32_e32 v207, v207
	v_add_f32_e32 v199, 1.0, v199
	v_add_f32_e32 v203, 1.0, v203
	v_add_f32_e32 v205, 1.0, v205
	v_add_f32_e32 v207, 1.0, v207
	v_rcp_f32_e32 v240, v199
	v_rcp_f32_e32 v241, v203
	v_rcp_f32_e32 v242, v205
	v_rcp_f32_e32 v243, v207
	v_pk_mul_f32 v[116:117], v[116:117], v[238:239] op_sel_hi:[1,0]
	v_pk_mul_f32 v[124:125], v[124:125], v[240:241]
	v_pk_mul_f32 v[120:121], v[120:121], v[238:239] op_sel_hi:[1,0]
	v_pk_mul_f32 v[118:119], v[118:119], v[238:239] op_sel_hi:[1,0]
	v_pk_mul_f32 v[126:127], v[126:127], v[242:243]
	v_pk_mul_f32 v[116:117], v[116:117], v[124:125]
	v_mul_f32_e32 v124, 0xbfb8aa3b, v120
	v_mul_f32_e32 v125, 0xbfb8aa3b, v121
	v_pk_mul_f32 v[122:123], v[122:123], v[238:239] op_sel_hi:[1,0]
	v_exp_f32_e32 v124, v124
	v_pk_mul_f32 v[118:119], v[118:119], v[126:127]
	v_exp_f32_e32 v125, v125
	v_mul_f32_e32 v126, 0xbfb8aa3b, v122
	v_mul_f32_e32 v127, 0xbfb8aa3b, v123
	v_exp_f32_e32 v126, v126
	v_exp_f32_e32 v127, v127
	v_add_f32_e32 v124, 1.0, v124
	v_add_f32_e32 v125, 1.0, v125
	v_rcp_f32_e32 v124, v124
	v_rcp_f32_e32 v125, v125
	v_add_f32_e32 v126, 1.0, v126
	v_add_f32_e32 v127, 1.0, v127
	v_rcp_f32_e32 v126, v126
	v_rcp_f32_e32 v127, v127
	v_pk_mul_f32 v[112:113], v[112:113], v[238:239] op_sel_hi:[1,0]
	v_pk_mul_f32 v[120:121], v[120:121], v[124:125]
	v_cmp_gt_f32_e32 vcc, s61, v236
	v_pk_mul_f32 v[120:121], v[112:113], v[120:121]
	v_pk_mul_f32 v[112:113], v[114:115], v[238:239] op_sel_hi:[1,0]
	v_pk_mul_f32 v[114:115], v[122:123], v[126:127]
	s_nop 0
	v_pk_mul_f32 v[122:123], v[112:113], v[114:115]
	v_mul_f32_e32 v113, 0x4b800000, v236
	v_cndmask_b32_e32 v113, v236, v113, vcc
	v_cvt_pk_bf16_f32 v112, v116, v117
; __device__ __forceinline__ u32x4 pk8(const f32x4 a, const f32x4 b) { u32x4 w; w.x = pk_bf16(a[0], a[1]); w.y = pk_bf16(a[2], a[3]); w.z = pk_bf16(b[0], b[1]); w.w = pk_bf16(b[2], b[3]); return w; }
; __device__ __forceinline__ float hsum4(const f32x4 v) { return (v[0] + v[1]) + (v[2] + v[3]); }
; __device__ __forceinline__ float fast_sigmoid(float x) { return __builtin_amdgcn_rcpf(1.0f + __expf(-x)); }
;     __device__ __forceinline__ void operator()(const f32x4 (&acc)[2][2][4][2], const Unit& u, int wr, int wc, int fr, int fq) const {
;     ...
;         for (int ai = 0; ai < 2; ++ai)
; #pragma unroll
;             for (int m = 0; m < 4; ++m) {
;                 const int row = rowb + ai * HALF + m * 16;
;                 float s = hsum4(p[ai][m][0]) + hsum4(p[ai][m][1]);
;                 s += __shfl_xor(s, 16); s += __shfl_xor(s, 32);
;                 const float rs = rsqrtf(s * (1.0f / DM) + EPS);
;                 f32x4 h[2];
; #pragma unroll
;                 for (int n = 0; n < 2; ++n)
; #pragma unroll
;                     for (int e = 0; e < 4; ++e) { const float a = acc[ai][0][m][n][e] * rs, b = acc[ai][1][m][n][e] * rs; h[n][e] = a * fast_sigmoid(a) * b; }
;                 __builtin_nontemporal_store(pk8(h[0], h[1]), (u32x4*)(H + (size_t)row * DFF + col));
	v_rsq_f32_e32 v116, v113
	v_cvt_pk_bf16_f32 v113, v118, v119
	v_cvt_pk_bf16_f32 v114, v120, v121
	v_cvt_pk_bf16_f32 v115, v122, v123
	v_mul_f32_e32 v117, 0x45800000, v116
	v_cndmask_b32_e32 v116, v116, v117, vcc
	v_pk_mul_f32 v[108:109], v[108:109], v[116:117] op_sel_hi:[1,0]
	global_store_dwordx4 v[228:229], v[112:115], off nt
	v_mul_f32_e32 v117, 0xbfb8aa3b, v108
	v_exp_f32_e32 v117, v117
	v_mul_f32_e32 v112, 0xbfb8aa3b, v109
	v_exp_f32_e32 v113, v112
	v_pk_mul_f32 v[110:111], v[110:111], v[116:117] op_sel_hi:[1,0]
	s_nop 0
	v_mul_f32_e32 v114, 0xbfb8aa3b, v110
	v_mul_f32_e32 v115, 0xbfb8aa3b, v111
	v_exp_f32_e32 v114, v114
	v_exp_f32_e32 v115, v115
	v_add_f32_e32 v112, 1.0, v117
	v_add_f32_e32 v113, 1.0, v113
	v_rcp_f32_e32 v112, v112
	v_rcp_f32_e32 v113, v113
	v_add_f32_e32 v114, 1.0, v114
	v_add_f32_e32 v115, 1.0, v115
	v_rcp_f32_e32 v114, v114
	v_rcp_f32_e32 v115, v115
	v_pk_mul_f32 v[100:101], v[100:101], v[116:117] op_sel_hi:[1,0]
	v_pk_mul_f32 v[108:109], v[108:109], v[112:113]
	v_pk_mul_f32 v[104:105], v[104:105], v[116:117] op_sel_hi:[1,0]
	v_pk_mul_f32 v[100:101], v[100:101], v[108:109]
	v_pk_mul_f32 v[108:109], v[110:111], v[114:115]
	v_mul_f32_e32 v110, 0xbfb8aa3b, v104
	v_exp_f32_e32 v110, v110
	v_pk_mul_f32 v[102:103], v[102:103], v[116:117] op_sel_hi:[1,0]
	v_pk_mul_f32 v[106:107], v[106:107], v[116:117] op_sel_hi:[1,0]
	v_pk_mul_f32 v[102:103], v[102:103], v[108:109]
	v_mul_f32_e32 v108, 0xbfb8aa3b, v105
	v_exp_f32_e32 v109, v108
	v_add_f32_e32 v108, 1.0, v110
	v_mul_f32_e32 v110, 0xbfb8aa3b, v106
	v_mul_f32_e32 v111, 0xbfb8aa3b, v107
	v_exp_f32_e32 v110, v110
	v_exp_f32_e32 v111, v111
	v_add_f32_e32 v109, 1.0, v109
	v_rcp_f32_e32 v108, v108
	v_rcp_f32_e32 v109, v109
	v_add_f32_e32 v110, 1.0, v110
	v_add_f32_e32 v111, 1.0, v111
	v_rcp_f32_e32 v110, v110
	v_rcp_f32_e32 v111, v111
	v_pk_mul_f32 v[96:97], v[96:97], v[116:117] op_sel_hi:[1,0]
	v_pk_mul_f32 v[104:105], v[104:105], v[108:109]
	s_waitcnt vmcnt(9)
	v_mov_b32_e32 v108, v222
	v_pk_mul_f32 v[104:105], v[96:97], v[104:105]
	v_pk_mul_f32 v[96:97], v[98:99], v[116:117] op_sel_hi:[1,0]
	v_pk_mul_f32 v[98:99], v[106:107], v[110:111]
	v_mov_b32_e32 v106, v220
	v_mov_b32_e32 v107, v232
	v_mov_b32_e32 v232, v221
	v_mov_b32_e32 v109, v234
	v_mov_b32_e32 v234, v223
	v_pk_add_f32 v[106:107], v[106:107], v[232:233]
	v_pk_add_f32 v[108:109], v[108:109], v[234:235]
	v_mov_b32_e32 v110, v166
	v_pk_add_f32 v[106:107], v[106:107], v[108:109]
	v_mov_b32_e32 v108, v164
	v_mov_b32_e32 v109, v160
	v_mov_b32_e32 v160, v165
	v_mov_b32_e32 v111, v162
	v_mov_b32_e32 v162, v167
	v_pk_add_f32 v[108:109], v[108:109], v[160:161]
	v_pk_add_f32 v[110:111], v[110:111], v[162:163]
	s_nop 0
	v_pk_add_f32 v[108:109], v[108:109], v[110:111]
	v_mov_b32_e32 v111, v106
	v_mov_b32_e32 v110, v108
	v_mov_b32_e32 v106, v109
	v_pk_add_f32 v[106:107], v[110:111], v[106:107]
	ds_bpermute_b32 v109, v195, v107
	ds_bpermute_b32 v108, v195, v106
	v_pk_mul_f32 v[110:111], v[96:97], v[98:99]
	v_cvt_pk_bf16_f32 v96, v100, v101
	v_cvt_pk_bf16_f32 v97, v102, v103
	v_cvt_pk_bf16_f32 v98, v104, v105
	s_waitcnt lgkmcnt(0)
	v_pk_add_f32 v[100:101], v[106:107], v[108:109]
	ds_bpermute_b32 v103, v191, v101
	ds_bpermute_b32 v102, v191, v100
	v_mad_i64_i32 v[104:105], s[14:15], v206, s60, v[188:189]
	v_cvt_pk_bf16_f32 v99, v110, v111
	v_lshl_add_u64 v[104:105], v[104:105], 0, v[192:193]
	s_waitcnt lgkmcnt(0)
	v_pk_add_f32 v[100:101], v[100:101], v[102:103]
	global_store_dwordx4 v[104:105], v[96:99], off nt
	v_pk_fma_f32 v[100:101], v[100:101], s[18:19], v[196:197] op_sel_hi:[1,0,0]
	s_nop 0
	v_mul_f32_e32 v102, 0x4b800000, v101
	v_cmp_gt_f32_e32 vcc, s61, v101
	v_mad_i64_i32 v[96:97], s[14:15], v208, s60, v[188:189]
	s_nop 0
	v_cndmask_b32_e32 v101, v101, v102, vcc
	v_rsq_f32_e32 v101, v101
	v_lshl_add_u64 v[96:97], v[96:97], 0, v[192:193]
	v_mul_f32_e32 v98, 0x45800000, v101
	v_cndmask_b32_e32 v98, v101, v98, vcc
	v_pk_mul_f32 v[92:93], v[92:93], v[98:99] op_sel_hi:[1,0]
	v_cmp_gt_f32_e32 vcc, s61, v100
	v_mul_f32_e32 v99, 0xbfb8aa3b, v92
	v_exp_f32_e32 v99, v99
	v_mul_f32_e32 v101, 0xbfb8aa3b, v93
	v_exp_f32_e32 v101, v101
	v_add_f32_e32 v99, 1.0, v99
	v_rcp_f32_e32 v102, v99
	v_pk_mul_f32 v[84:85], v[84:85], v[98:99] op_sel_hi:[1,0]
	v_add_f32_e32 v99, 1.0, v101
	v_pk_mul_f32 v[94:95], v[94:95], v[98:99] op_sel_hi:[1,0]
	s_nop 0
	v_mul_f32_e32 v101, 0xbfb8aa3b, v94
	v_exp_f32_e32 v101, v101
	v_mul_f32_e32 v103, 0xbfb8aa3b, v95
	v_exp_f32_e32 v105, v103
	v_rcp_f32_e32 v103, v99
	v_add_f32_e32 v99, 1.0, v101
	v_rcp_f32_e32 v104, v99
	v_add_f32_e32 v99, 1.0, v105
	v_rcp_f32_e32 v105, v99
	v_pk_mul_f32 v[92:93], v[92:93], v[102:103]
	v_pk_mul_f32 v[88:89], v[88:89], v[98:99] op_sel_hi:[1,0]
	v_pk_mul_f32 v[84:85], v[84:85], v[92:93]
	v_pk_mul_f32 v[92:93], v[94:95], v[104:105]
	v_mul_f32_e32 v94, 0xbfb8aa3b, v88
	v_exp_f32_e32 v94, v94
	v_pk_mul_f32 v[86:87], v[86:87], v[98:99] op_sel_hi:[1,0]
	v_pk_mul_f32 v[90:91], v[90:91], v[98:99] op_sel_hi:[1,0]
	v_pk_mul_f32 v[86:87], v[86:87], v[92:93]
	v_mul_f32_e32 v92, 0xbfb8aa3b, v89
	v_exp_f32_e32 v93, v92
	v_add_f32_e32 v92, 1.0, v94
	v_mul_f32_e32 v94, 0xbfb8aa3b, v90
	v_mul_f32_e32 v95, 0xbfb8aa3b, v91
	v_exp_f32_e32 v94, v94
	v_exp_f32_e32 v95, v95
	v_add_f32_e32 v93, 1.0, v93
	v_rcp_f32_e32 v92, v92
	v_rcp_f32_e32 v93, v93
	v_add_f32_e32 v94, 1.0, v94
	v_add_f32_e32 v95, 1.0, v95
	v_rcp_f32_e32 v94, v94
	v_rcp_f32_e32 v95, v95
	v_pk_mul_f32 v[80:81], v[80:81], v[98:99] op_sel_hi:[1,0]
	v_pk_mul_f32 v[88:89], v[88:89], v[92:93]
	s_nop 0
	v_pk_mul_f32 v[88:89], v[80:81], v[88:89]
	v_pk_mul_f32 v[80:81], v[82:83], v[98:99] op_sel_hi:[1,0]
	v_pk_mul_f32 v[82:83], v[90:91], v[94:95]
; __device__ __forceinline__ u32x4 pk8(const f32x4 a, const f32x4 b) { u32x4 w; w.x = pk_bf16(a[0], a[1]); w.y = pk_bf16(a[2], a[3]); w.z = pk_bf16(b[0], b[1]); w.w = pk_bf16(b[2], b[3]); return w; }
; __device__ __forceinline__ float hsum4(const f32x4 v) { return (v[0] + v[1]) + (v[2] + v[3]); }
; __device__ __forceinline__ float fast_sigmoid(float x) { return __builtin_amdgcn_rcpf(1.0f + __expf(-x)); }
;     __device__ __forceinline__ void operator()(const f32x4 (&acc)[2][2][4][2], const Unit& u, int wr, int wc, int fr, int fq) const {
;     ...
;         for (int ai = 0; ai < 2; ++ai)
; #pragma unroll
;             for (int m = 0; m < 4; ++m) {
;                 const int row = rowb + ai * HALF + m * 16;
;                 float s = hsum4(p[ai][m][0]) + hsum4(p[ai][m][1]);
;                 s += __shfl_xor(s, 16); s += __shfl_xor(s, 32);
;                 const float rs = rsqrtf(s * (1.0f / DM) + EPS);
;                 f32x4 h[2];
; #pragma unroll
;                 for (int n = 0; n < 2; ++n)
; #pragma unroll
;                     for (int e = 0; e < 4; ++e) { const float a = acc[ai][0][m][n][e] * rs, b = acc[ai][1][m][n][e] * rs; h[n][e] = a * fast_sigmoid(a) * b; }
;                 __builtin_nontemporal_store(pk8(h[0], h[1]), (u32x4*)(H + (size_t)row * DFF + col));
	s_nop 0
	v_pk_mul_f32 v[90:91], v[80:81], v[82:83]
	v_mul_f32_e32 v81, 0x4b800000, v100
	v_cndmask_b32_e32 v81, v100, v81, vcc
	v_cvt_pk_bf16_f32 v80, v84, v85
	v_rsq_f32_e32 v84, v81
	v_cvt_pk_bf16_f32 v81, v86, v87
	v_cvt_pk_bf16_f32 v82, v88, v89
	v_cvt_pk_bf16_f32 v83, v90, v91
	v_mul_f32_e32 v85, 0x45800000, v84
	v_cndmask_b32_e32 v84, v84, v85, vcc
	v_pk_mul_f32 v[76:77], v[76:77], v[84:85] op_sel_hi:[1,0]
	global_store_dwordx4 v[96:97], v[80:83], off nt
	v_mul_f32_e32 v85, 0xbfb8aa3b, v76
	v_exp_f32_e32 v85, v85
	v_mul_f32_e32 v80, 0xbfb8aa3b, v77
	v_exp_f32_e32 v81, v80
	v_pk_mul_f32 v[78:79], v[78:79], v[84:85] op_sel_hi:[1,0]
	s_nop 0
	v_mul_f32_e32 v82, 0xbfb8aa3b, v78
	v_mul_f32_e32 v83, 0xbfb8aa3b, v79
	v_exp_f32_e32 v82, v82
	v_exp_f32_e32 v83, v83
	v_add_f32_e32 v80, 1.0, v85
	v_add_f32_e32 v81, 1.0, v81
	v_rcp_f32_e32 v80, v80
	v_rcp_f32_e32 v81, v81
	v_add_f32_e32 v82, 1.0, v82
	v_add_f32_e32 v83, 1.0, v83
	v_rcp_f32_e32 v82, v82
	v_rcp_f32_e32 v83, v83
	v_pk_mul_f32 v[68:69], v[68:69], v[84:85] op_sel_hi:[1,0]
	v_pk_mul_f32 v[76:77], v[76:77], v[80:81]
	v_pk_mul_f32 v[72:73], v[72:73], v[84:85] op_sel_hi:[1,0]
	v_pk_mul_f32 v[68:69], v[68:69], v[76:77]
	v_pk_mul_f32 v[76:77], v[78:79], v[82:83]
	v_mul_f32_e32 v78, 0xbfb8aa3b, v72
	v_exp_f32_e32 v78, v78
	v_pk_mul_f32 v[70:71], v[70:71], v[84:85] op_sel_hi:[1,0]
	v_pk_mul_f32 v[74:75], v[74:75], v[84:85] op_sel_hi:[1,0]
	v_pk_mul_f32 v[70:71], v[70:71], v[76:77]
	v_mul_f32_e32 v76, 0xbfb8aa3b, v73
	v_exp_f32_e32 v77, v76
	v_add_f32_e32 v76, 1.0, v78
	v_mul_f32_e32 v78, 0xbfb8aa3b, v74
	v_mul_f32_e32 v79, 0xbfb8aa3b, v75
	v_exp_f32_e32 v78, v78
	v_exp_f32_e32 v79, v79
	v_add_f32_e32 v77, 1.0, v77
	v_rcp_f32_e32 v76, v76
	v_rcp_f32_e32 v77, v77
	v_add_f32_e32 v78, 1.0, v78
	v_add_f32_e32 v79, 1.0, v79
	v_rcp_f32_e32 v78, v78
	v_rcp_f32_e32 v79, v79
	v_pk_mul_f32 v[64:65], v[64:65], v[84:85] op_sel_hi:[1,0]
	v_pk_mul_f32 v[72:73], v[72:73], v[76:77]
	s_waitcnt vmcnt(10)
	v_mov_b32_e32 v76, v158
	v_pk_mul_f32 v[72:73], v[64:65], v[72:73]
	v_pk_mul_f32 v[64:65], v[66:67], v[84:85] op_sel_hi:[1,0]
	v_pk_mul_f32 v[66:67], v[74:75], v[78:79]
	v_mov_b32_e32 v74, v156
	s_waitcnt vmcnt(9)
	v_mov_b32_e32 v75, v152
	v_mov_b32_e32 v152, v157
	v_mov_b32_e32 v77, v154
	v_mov_b32_e32 v154, v159
	v_pk_add_f32 v[74:75], v[74:75], v[152:153]
	v_pk_add_f32 v[76:77], v[76:77], v[154:155]
	s_waitcnt vmcnt(8)
	v_mov_b32_e32 v78, v150
	v_pk_add_f32 v[74:75], v[74:75], v[76:77]
	v_mov_b32_e32 v76, v148
	s_waitcnt vmcnt(7)
	v_mov_b32_e32 v77, v144
	v_mov_b32_e32 v144, v149
	v_mov_b32_e32 v79, v146
	v_mov_b32_e32 v146, v151
	v_pk_add_f32 v[76:77], v[76:77], v[144:145]
	v_pk_add_f32 v[78:79], v[78:79], v[146:147]
	s_nop 0
	v_pk_add_f32 v[76:77], v[76:77], v[78:79]
	v_mov_b32_e32 v79, v74
	v_mov_b32_e32 v78, v76
	v_mov_b32_e32 v74, v77
	v_pk_add_f32 v[74:75], v[78:79], v[74:75]
	ds_bpermute_b32 v77, v195, v75
	ds_bpermute_b32 v76, v195, v74
	v_pk_mul_f32 v[78:79], v[64:65], v[66:67]
	v_cvt_pk_bf16_f32 v64, v68, v69
	v_cvt_pk_bf16_f32 v65, v70, v71
	v_cvt_pk_bf16_f32 v66, v72, v73
	s_waitcnt lgkmcnt(0)
	v_pk_add_f32 v[68:69], v[74:75], v[76:77]
	ds_bpermute_b32 v71, v191, v69
	ds_bpermute_b32 v70, v191, v68
	v_mad_i64_i32 v[72:73], s[14:15], v204, s60, v[188:189]
	v_cvt_pk_bf16_f32 v67, v78, v79
	v_lshl_add_u64 v[72:73], v[72:73], 0, v[192:193]
	s_waitcnt lgkmcnt(0)
	v_pk_add_f32 v[68:69], v[68:69], v[70:71]
	global_store_dwordx4 v[72:73], v[64:67], off nt
	v_pk_fma_f32 v[68:69], v[68:69], s[18:19], v[196:197] op_sel_hi:[1,0,0]
	s_nop 0
	v_mul_f32_e32 v70, 0x4b800000, v69
	v_cmp_gt_f32_e32 vcc, s61, v69
	v_mad_i64_i32 v[64:65], s[14:15], v202, s60, v[188:189]
	s_nop 0
	v_cndmask_b32_e32 v69, v69, v70, vcc
	v_rsq_f32_e32 v69, v69
	v_lshl_add_u64 v[64:65], v[64:65], 0, v[192:193]
	v_mul_f32_e32 v66, 0x45800000, v69
	v_cndmask_b32_e32 v66, v69, v66, vcc
	v_pk_mul_f32 v[60:61], v[60:61], v[66:67] op_sel_hi:[1,0]
	v_cmp_gt_f32_e32 vcc, s61, v68
	v_mul_f32_e32 v67, 0xbfb8aa3b, v60
	v_exp_f32_e32 v67, v67
	v_mul_f32_e32 v69, 0xbfb8aa3b, v61
	v_exp_f32_e32 v69, v69
	v_add_f32_e32 v67, 1.0, v67
	v_rcp_f32_e32 v70, v67
	v_pk_mul_f32 v[52:53], v[52:53], v[66:67] op_sel_hi:[1,0]
	v_add_f32_e32 v67, 1.0, v69
	v_pk_mul_f32 v[62:63], v[62:63], v[66:67] op_sel_hi:[1,0]
	s_nop 0
	v_mul_f32_e32 v69, 0xbfb8aa3b, v62
	v_exp_f32_e32 v69, v69
	v_mul_f32_e32 v71, 0xbfb8aa3b, v63
	v_exp_f32_e32 v73, v71
	v_rcp_f32_e32 v71, v67
	v_add_f32_e32 v67, 1.0, v69
	v_rcp_f32_e32 v72, v67
	v_add_f32_e32 v67, 1.0, v73
	v_rcp_f32_e32 v73, v67
	v_pk_mul_f32 v[60:61], v[60:61], v[70:71]
	v_pk_mul_f32 v[56:57], v[56:57], v[66:67] op_sel_hi:[1,0]
	v_pk_mul_f32 v[52:53], v[52:53], v[60:61]
	v_pk_mul_f32 v[60:61], v[62:63], v[72:73]
	v_mul_f32_e32 v62, 0xbfb8aa3b, v56
	v_exp_f32_e32 v62, v62
	v_pk_mul_f32 v[54:55], v[54:55], v[66:67] op_sel_hi:[1,0]
	v_pk_mul_f32 v[58:59], v[58:59], v[66:67] op_sel_hi:[1,0]
	v_pk_mul_f32 v[54:55], v[54:55], v[60:61]
	v_mul_f32_e32 v60, 0xbfb8aa3b, v57
	v_exp_f32_e32 v61, v60
	v_add_f32_e32 v60, 1.0, v62
	v_mul_f32_e32 v62, 0xbfb8aa3b, v58
	v_mul_f32_e32 v63, 0xbfb8aa3b, v59
	v_exp_f32_e32 v62, v62
	v_exp_f32_e32 v63, v63
	v_add_f32_e32 v61, 1.0, v61
	v_rcp_f32_e32 v60, v60
	v_rcp_f32_e32 v61, v61
	v_add_f32_e32 v62, 1.0, v62
	v_add_f32_e32 v63, 1.0, v63
	v_rcp_f32_e32 v62, v62
	v_rcp_f32_e32 v63, v63
	v_pk_mul_f32 v[48:49], v[48:49], v[66:67] op_sel_hi:[1,0]
	v_pk_mul_f32 v[56:57], v[56:57], v[60:61]
	s_nop 0
	v_pk_mul_f32 v[56:57], v[48:49], v[56:57]
	v_pk_mul_f32 v[48:49], v[50:51], v[66:67] op_sel_hi:[1,0]
	v_pk_mul_f32 v[50:51], v[58:59], v[62:63]
	s_nop 0
	v_pk_mul_f32 v[58:59], v[48:49], v[50:51]
; __device__ __forceinline__ u32x4 pk8(const f32x4 a, const f32x4 b) { u32x4 w; w.x = pk_bf16(a[0], a[1]); w.y = pk_bf16(a[2], a[3]); w.z = pk_bf16(b[0], b[1]); w.w = pk_bf16(b[2], b[3]); return w; }
; __device__ __forceinline__ float hsum4(const f32x4 v) { return (v[0] + v[1]) + (v[2] + v[3]); }
; __device__ __forceinline__ float fast_sigmoid(float x) { return __builtin_amdgcn_rcpf(1.0f + __expf(-x)); }
;     __device__ __forceinline__ void operator()(const f32x4 (&acc)[2][2][4][2], const Unit& u, int wr, int wc, int fr, int fq) const {
;     ...
;         for (int ai = 0; ai < 2; ++ai)
; #pragma unroll
;             for (int m = 0; m < 4; ++m) {
;                 const int row = rowb + ai * HALF + m * 16;
;                 float s = hsum4(p[ai][m][0]) + hsum4(p[ai][m][1]);
;                 s += __shfl_xor(s, 16); s += __shfl_xor(s, 32);
;                 const float rs = rsqrtf(s * (1.0f / DM) + EPS);
;                 f32x4 h[2];
; #pragma unroll
;                 for (int n = 0; n < 2; ++n)
; #pragma unroll
;                     for (int e = 0; e < 4; ++e) { const float a = acc[ai][0][m][n][e] * rs, b = acc[ai][1][m][n][e] * rs; h[n][e] = a * fast_sigmoid(a) * b; }
;                 __builtin_nontemporal_store(pk8(h[0], h[1]), (u32x4*)(H + (size_t)row * DFF + col));
	v_mul_f32_e32 v49, 0x4b800000, v68
	v_cndmask_b32_e32 v49, v68, v49, vcc
	v_cvt_pk_bf16_f32 v48, v52, v53
	v_rsq_f32_e32 v52, v49
	v_cvt_pk_bf16_f32 v49, v54, v55
	v_cvt_pk_bf16_f32 v50, v56, v57
	v_cvt_pk_bf16_f32 v51, v58, v59
	v_mul_f32_e32 v53, 0x45800000, v52
	v_cndmask_b32_e32 v52, v52, v53, vcc
	v_pk_mul_f32 v[44:45], v[44:45], v[52:53] op_sel_hi:[1,0]
	global_store_dwordx4 v[64:65], v[48:51], off nt
	v_mul_f32_e32 v53, 0xbfb8aa3b, v44
	v_exp_f32_e32 v53, v53
	v_mul_f32_e32 v48, 0xbfb8aa3b, v45
	v_exp_f32_e32 v49, v48
	v_pk_mul_f32 v[46:47], v[46:47], v[52:53] op_sel_hi:[1,0]
	s_nop 0
	v_mul_f32_e32 v50, 0xbfb8aa3b, v46
	v_mul_f32_e32 v51, 0xbfb8aa3b, v47
	v_exp_f32_e32 v50, v50
	v_exp_f32_e32 v51, v51
	v_add_f32_e32 v48, 1.0, v53
	v_add_f32_e32 v49, 1.0, v49
	v_rcp_f32_e32 v48, v48
	v_rcp_f32_e32 v49, v49
	v_add_f32_e32 v50, 1.0, v50
	v_add_f32_e32 v51, 1.0, v51
	v_rcp_f32_e32 v50, v50
	v_rcp_f32_e32 v51, v51
	v_pk_mul_f32 v[36:37], v[36:37], v[52:53] op_sel_hi:[1,0]
	v_pk_mul_f32 v[44:45], v[44:45], v[48:49]
	v_pk_mul_f32 v[40:41], v[40:41], v[52:53] op_sel_hi:[1,0]
	v_pk_mul_f32 v[36:37], v[36:37], v[44:45]
	v_pk_mul_f32 v[44:45], v[46:47], v[50:51]
	v_mul_f32_e32 v46, 0xbfb8aa3b, v40
	v_exp_f32_e32 v46, v46
	v_pk_mul_f32 v[38:39], v[38:39], v[52:53] op_sel_hi:[1,0]
	v_pk_mul_f32 v[42:43], v[42:43], v[52:53] op_sel_hi:[1,0]
	v_pk_mul_f32 v[38:39], v[38:39], v[44:45]
	v_mul_f32_e32 v44, 0xbfb8aa3b, v41
	v_exp_f32_e32 v45, v44
	v_add_f32_e32 v44, 1.0, v46
	v_mul_f32_e32 v46, 0xbfb8aa3b, v42
	v_mul_f32_e32 v47, 0xbfb8aa3b, v43
	v_exp_f32_e32 v46, v46
	v_exp_f32_e32 v47, v47
	v_add_f32_e32 v45, 1.0, v45
	v_rcp_f32_e32 v44, v44
	v_rcp_f32_e32 v45, v45
	v_add_f32_e32 v46, 1.0, v46
	v_add_f32_e32 v47, 1.0, v47
	v_rcp_f32_e32 v46, v46
	v_rcp_f32_e32 v47, v47
	v_pk_mul_f32 v[32:33], v[32:33], v[52:53] op_sel_hi:[1,0]
	v_pk_mul_f32 v[40:41], v[40:41], v[44:45]
	s_waitcnt vmcnt(8)
	v_mov_b32_e32 v44, v142
	v_pk_mul_f32 v[40:41], v[32:33], v[40:41]
	v_pk_mul_f32 v[32:33], v[34:35], v[52:53] op_sel_hi:[1,0]
	v_pk_mul_f32 v[34:35], v[42:43], v[46:47]
	v_mov_b32_e32 v42, v140
	s_waitcnt vmcnt(7)
	v_mov_b32_e32 v43, v136
	v_mov_b32_e32 v136, v141
	v_mov_b32_e32 v45, v138
	v_mov_b32_e32 v138, v143
	v_pk_add_f32 v[42:43], v[42:43], v[136:137]
	v_pk_add_f32 v[44:45], v[44:45], v[138:139]
	s_waitcnt vmcnt(6)
	v_mov_b32_e32 v46, v134
	v_pk_add_f32 v[42:43], v[42:43], v[44:45]
	v_mov_b32_e32 v44, v132
	s_waitcnt vmcnt(5)
	v_mov_b32_e32 v45, v128
	v_mov_b32_e32 v128, v133
	v_mov_b32_e32 v47, v130
	v_mov_b32_e32 v130, v135
	v_pk_add_f32 v[44:45], v[44:45], v[128:129]
	v_pk_add_f32 v[46:47], v[46:47], v[130:131]
	s_nop 0
	v_pk_add_f32 v[44:45], v[44:45], v[46:47]
	v_mov_b32_e32 v47, v42
	v_mov_b32_e32 v46, v44
	v_mov_b32_e32 v42, v45
	v_pk_add_f32 v[42:43], v[46:47], v[42:43]
	ds_bpermute_b32 v45, v195, v43
	ds_bpermute_b32 v44, v195, v42
	v_pk_mul_f32 v[46:47], v[32:33], v[34:35]
	v_cvt_pk_bf16_f32 v32, v36, v37
	v_cvt_pk_bf16_f32 v33, v38, v39
	v_cvt_pk_bf16_f32 v34, v40, v41
	s_waitcnt lgkmcnt(0)
	v_pk_add_f32 v[36:37], v[42:43], v[44:45]
	ds_bpermute_b32 v39, v191, v37
	ds_bpermute_b32 v38, v191, v36
	v_mad_i64_i32 v[40:41], s[14:15], v198, s60, v[188:189]
	v_cvt_pk_bf16_f32 v35, v46, v47
	v_lshl_add_u64 v[40:41], v[40:41], 0, v[192:193]
	s_waitcnt lgkmcnt(0)
; #define PG8_BAR __builtin_amdgcn_s_barrier()
; __device__ __forceinline__ u32x4 pk8(const f32x4 a, const f32x4 b) { u32x4 w; w.x = pk_bf16(a[0], a[1]); w.y = pk_bf16(a[2], a[3]); w.z = pk_bf16(b[0], b[1]); w.w = pk_bf16(b[2], b[3]); return w; }
; __device__ __forceinline__ float hsum4(const f32x4 v) { return (v[0] + v[1]) + (v[2] + v[3]); }
; __device__ __forceinline__ float fast_sigmoid(float x) { return __builtin_amdgcn_rcpf(1.0f + __expf(-x)); }
; template <class Epi, class Sched, bool ALIGN_EPI = false, bool SP2 = false, bool DUAL = false>
; __device__ __forceinline__ void gemm_phase(PG8_LAS unsigned char* lds, const Gemm g, const Sched& S, const Epi& E) {
;     ...
;         if (!has_next) break;
;         if (!keep)
; #pragma unroll
;         for (int a = 0; a < 2; ++a)
; #pragma unroll
;             for (int b = 0; b < 2; ++b)
; #pragma unroll
;                 for (int m = 0; m < 4; ++m)
; #pragma unroll
;                     for (int n = 0; n < 2; ++n) acc[a][b][m][n] = (f32x4){0.f, 0.f, 0.f, 0.f};
;         cur = nxt; cA = nA; cB = nB; ++ui;
;         if constexpr (ALIGN_EPI) { if (wr == 1) PG8_BAR; }
;     __device__ __forceinline__ void operator()(const f32x4 (&acc)[2][2][4][2], const Unit& u, int wr, int wc, int fr, int fq) const {
;     ...
;         for (int ai = 0; ai < 2; ++ai)
; #pragma unroll
;             for (int m = 0; m < 4; ++m) {
;                 const int row = rowb + ai * HALF + m * 16;
;                 float s = hsum4(p[ai][m][0]) + hsum4(p[ai][m][1]);
;                 s += __shfl_xor(s, 16); s += __shfl_xor(s, 32);
;                 const float rs = rsqrtf(s * (1.0f / DM) + EPS);
;                 f32x4 h[2];
; #pragma unroll
;                 for (int n = 0; n < 2; ++n)
; #pragma unroll
;                     for (int e = 0; e < 4; ++e) { const float a = acc[ai][0][m][n][e] * rs, b = acc[ai][1][m][n][e] * rs; h[n][e] = a * fast_sigmoid(a) * b; }
;                 __builtin_nontemporal_store(pk8(h[0], h[1]), (u32x4*)(H + (size_t)row * DFF + col));
	v_pk_add_f32 v[36:37], v[36:37], v[38:39]
	global_store_dwordx4 v[40:41], v[32:35], off nt
	v_pk_fma_f32 v[36:37], v[36:37], s[18:19], v[196:197] op_sel_hi:[1,0,0]
	s_nop 0
	v_mul_f32_e32 v38, 0x4b800000, v37
	v_cmp_gt_f32_e32 vcc, s61, v37
	v_mad_i64_i32 v[32:33], s[14:15], v194, s60, v[188:189]
	s_nop 0
	v_cndmask_b32_e32 v37, v37, v38, vcc
	v_rsq_f32_e32 v37, v37
	v_lshl_add_u64 v[32:33], v[32:33], 0, v[192:193]
	v_mul_f32_e32 v34, 0x45800000, v37
	v_cndmask_b32_e32 v34, v37, v34, vcc
	v_pk_mul_f32 v[28:29], v[28:29], v[34:35] op_sel_hi:[1,0]
	v_cmp_gt_f32_e32 vcc, s61, v36
	v_mul_f32_e32 v35, 0xbfb8aa3b, v28
	v_exp_f32_e32 v35, v35
	v_mul_f32_e32 v37, 0xbfb8aa3b, v29
	v_exp_f32_e32 v37, v37
	v_add_f32_e32 v35, 1.0, v35
	v_rcp_f32_e32 v38, v35
	v_pk_mul_f32 v[20:21], v[20:21], v[34:35] op_sel_hi:[1,0]
	v_add_f32_e32 v35, 1.0, v37
	v_pk_mul_f32 v[30:31], v[30:31], v[34:35] op_sel_hi:[1,0]
	s_nop 0
	v_mul_f32_e32 v37, 0xbfb8aa3b, v30
	v_exp_f32_e32 v37, v37
	v_mul_f32_e32 v39, 0xbfb8aa3b, v31
	v_exp_f32_e32 v41, v39
	v_rcp_f32_e32 v39, v35
	v_add_f32_e32 v35, 1.0, v37
	v_rcp_f32_e32 v40, v35
	v_add_f32_e32 v35, 1.0, v41
	v_rcp_f32_e32 v41, v35
	v_pk_mul_f32 v[28:29], v[28:29], v[38:39]
	v_pk_mul_f32 v[24:25], v[24:25], v[34:35] op_sel_hi:[1,0]
	v_pk_mul_f32 v[20:21], v[20:21], v[28:29]
	v_pk_mul_f32 v[28:29], v[30:31], v[40:41]
	v_mul_f32_e32 v30, 0xbfb8aa3b, v24
	v_exp_f32_e32 v30, v30
	v_pk_mul_f32 v[22:23], v[22:23], v[34:35] op_sel_hi:[1,0]
	v_pk_mul_f32 v[26:27], v[26:27], v[34:35] op_sel_hi:[1,0]
	v_pk_mul_f32 v[22:23], v[22:23], v[28:29]
	v_mul_f32_e32 v28, 0xbfb8aa3b, v25
	v_exp_f32_e32 v29, v28
	v_add_f32_e32 v28, 1.0, v30
	v_mul_f32_e32 v30, 0xbfb8aa3b, v26
	v_mul_f32_e32 v31, 0xbfb8aa3b, v27
	v_exp_f32_e32 v30, v30
	v_exp_f32_e32 v31, v31
	v_add_f32_e32 v29, 1.0, v29
	v_rcp_f32_e32 v28, v28
	v_rcp_f32_e32 v29, v29
	v_add_f32_e32 v30, 1.0, v30
	v_add_f32_e32 v31, 1.0, v31
	v_rcp_f32_e32 v30, v30
	v_rcp_f32_e32 v31, v31
	v_pk_mul_f32 v[16:17], v[16:17], v[34:35] op_sel_hi:[1,0]
	v_pk_mul_f32 v[24:25], v[24:25], v[28:29]
	s_nop 0
	v_pk_mul_f32 v[24:25], v[16:17], v[24:25]
	v_pk_mul_f32 v[16:17], v[18:19], v[34:35] op_sel_hi:[1,0]
	v_pk_mul_f32 v[18:19], v[26:27], v[30:31]
	s_nop 0
	v_pk_mul_f32 v[26:27], v[16:17], v[18:19]
	v_mul_f32_e32 v17, 0x4b800000, v36
	v_cndmask_b32_e32 v17, v36, v17, vcc
	v_cvt_pk_bf16_f32 v16, v20, v21
	v_rsq_f32_e32 v20, v17
	v_cvt_pk_bf16_f32 v17, v22, v23
	v_cvt_pk_bf16_f32 v18, v24, v25
	v_cvt_pk_bf16_f32 v19, v26, v27
	v_mul_f32_e32 v21, 0x45800000, v20
	v_cndmask_b32_e32 v20, v20, v21, vcc
	v_pk_mul_f32 v[12:13], v[12:13], v[20:21] op_sel_hi:[1,0]
	global_store_dwordx4 v[32:33], v[16:19], off nt
	v_mul_f32_e32 v21, 0xbfb8aa3b, v12
	v_exp_f32_e32 v21, v21
	v_mul_f32_e32 v16, 0xbfb8aa3b, v13
	v_exp_f32_e32 v17, v16
	s_andn2_b64 vcc, exec, s[4:5]
	v_pk_mul_f32 v[14:15], v[14:15], v[20:21] op_sel_hi:[1,0]
	v_add_f32_e32 v16, 1.0, v21
	v_mul_f32_e32 v18, 0xbfb8aa3b, v14
	v_mul_f32_e32 v19, 0xbfb8aa3b, v15
	v_exp_f32_e32 v18, v18
	v_exp_f32_e32 v19, v19
	v_add_f32_e32 v17, 1.0, v17
	v_rcp_f32_e32 v16, v16
	v_rcp_f32_e32 v17, v17
	v_add_f32_e32 v18, 1.0, v18
	v_add_f32_e32 v19, 1.0, v19
	v_rcp_f32_e32 v18, v18
	v_rcp_f32_e32 v19, v19
	v_pk_mul_f32 v[4:5], v[4:5], v[20:21] op_sel_hi:[1,0]
	v_pk_mul_f32 v[12:13], v[12:13], v[16:17]
	v_pk_mul_f32 v[8:9], v[8:9], v[20:21] op_sel_hi:[1,0]
	v_pk_mul_f32 v[4:5], v[4:5], v[12:13]
	v_pk_mul_f32 v[12:13], v[14:15], v[18:19]
	v_mul_f32_e32 v14, 0xbfb8aa3b, v8
	v_exp_f32_e32 v14, v14
	v_pk_mul_f32 v[6:7], v[6:7], v[20:21] op_sel_hi:[1,0]
	v_pk_mul_f32 v[10:11], v[10:11], v[20:21] op_sel_hi:[1,0]
	v_pk_mul_f32 v[6:7], v[6:7], v[12:13]
	v_mul_f32_e32 v12, 0xbfb8aa3b, v9
	v_exp_f32_e32 v13, v12
	v_add_f32_e32 v12, 1.0, v14
	v_mul_f32_e32 v14, 0xbfb8aa3b, v10
	v_mul_f32_e32 v15, 0xbfb8aa3b, v11
	v_exp_f32_e32 v14, v14
	v_exp_f32_e32 v15, v15
	v_add_f32_e32 v13, 1.0, v13
	v_rcp_f32_e32 v12, v12
	v_rcp_f32_e32 v13, v13
	v_add_f32_e32 v14, 1.0, v14
	v_add_f32_e32 v15, 1.0, v15
	v_rcp_f32_e32 v14, v14
	v_rcp_f32_e32 v15, v15
	v_pk_mul_f32 v[0:1], v[0:1], v[20:21] op_sel_hi:[1,0]
	v_pk_mul_f32 v[8:9], v[8:9], v[12:13]
	s_mov_b64 s[4:5], -1
	v_pk_mul_f32 v[8:9], v[0:1], v[8:9]
	v_pk_mul_f32 v[0:1], v[2:3], v[20:21] op_sel_hi:[1,0]
	v_pk_mul_f32 v[2:3], v[10:11], v[14:15]
	s_nop 0
	v_pk_mul_f32 v[10:11], v[0:1], v[2:3]
	v_cvt_pk_bf16_f32 v0, v4, v5
	v_mad_i64_i32 v[4:5], s[14:15], v190, s60, v[188:189]
	v_cvt_pk_bf16_f32 v1, v6, v7
	v_cvt_pk_bf16_f32 v2, v8, v9
	v_cvt_pk_bf16_f32 v3, v10, v11
	v_lshl_add_u64 v[4:5], v[4:5], 0, v[192:193]
	global_store_dwordx4 v[4:5], v[0:3], off nt
	s_cbranch_vccnz .LBB0_984
	s_andn2_b64 vcc, exec, s[6:7]
	s_cbranch_vccnz .LBB0_983
	s_barrier
	s_branch .LBB0_983
